# v27: v24 + grid-barrier waiters poll the top-level generation word directly (skip the per-XCC release hop)
# speedup vs baseline: 1.0069x; 1.0069x over previous
.LBB0_96:
	s_or_b64 exec, exec, s[10:11]
	s_cmp_eq_u32 s0, 0
	s_cselect_b64 vcc, -1, 0
	s_cmp_eq_u32 s0, 1
	v_cndmask_b32_e32 v18, 1, v15, vcc
	s_cselect_b64 vcc, -1, 0
	s_cmp_eq_u32 s0, 2
	v_cndmask_b32_e32 v18, v18, v0, vcc
	s_cselect_b64 vcc, -1, 0
	s_cmp_eq_u32 s0, 3
	v_cndmask_b32_e32 v18, v18, v1, vcc
	s_cselect_b64 vcc, -1, 0
	s_cmp_eq_u32 s0, 4
	v_cndmask_b32_e32 v18, v18, v2, vcc
	s_cselect_b64 vcc, -1, 0
	s_cmp_eq_u32 s0, 5
	v_cndmask_b32_e32 v18, v18, v3, vcc
	s_cselect_b64 vcc, -1, 0
	s_cmp_eq_u32 s0, 6
	v_cndmask_b32_e32 v18, v18, v4, vcc
	s_cselect_b64 vcc, -1, 0
	s_cmp_eq_u32 s0, 7
	v_cndmask_b32_e32 v18, v18, v5, vcc
	s_cselect_b64 vcc, -1, 0
	s_cmp_eq_u32 s0, 8
	v_cndmask_b32_e32 v18, v18, v6, vcc
	s_cselect_b64 vcc, -1, 0
	s_cmp_eq_u32 s0, 9
	v_cndmask_b32_e32 v18, v18, v7, vcc
	s_cselect_b64 vcc, -1, 0
	s_cmp_eq_u32 s0, 10
	v_cndmask_b32_e32 v18, v18, v8, vcc
	s_cselect_b64 vcc, -1, 0
	s_cmp_eq_u32 s0, 11
	v_cndmask_b32_e32 v18, v18, v9, vcc
	s_cselect_b64 vcc, -1, 0
	s_cmp_eq_u32 s0, 12
	v_cndmask_b32_e32 v18, v18, v10, vcc
	s_cselect_b64 vcc, -1, 0
	s_cmp_eq_u32 s0, 13
	v_cndmask_b32_e32 v18, v18, v11, vcc
	s_cselect_b64 vcc, -1, 0
	s_cmp_eq_u32 s0, 14
	v_cndmask_b32_e32 v18, v18, v12, vcc
	s_cselect_b64 vcc, -1, 0
	s_cmp_eq_u32 s0, 15
	v_cndmask_b32_e32 v18, v18, v13, vcc
	s_cselect_b64 vcc, -1, 0
	v_cndmask_b32_e32 v18, v18, v14, vcc
	v_cvt_f32_u32_e32 v19, v18
	s_waitcnt vmcnt(0)
	v_readfirstlane_b32 s0, v17
	v_rcp_iflag_f32_e32 v19, v19
	s_nop 0
	v_add_u32_e32 v17, s0, v16
	v_sub_u32_e32 v16, 0, v18
	v_mul_f32_e32 v19, 0x4f7ffffe, v19
	v_cvt_u32_f32_e32 v19, v19
	v_mul_lo_u32 v16, v16, v19
	v_mul_hi_u32 v16, v19, v16
	v_add_u32_e32 v16, v19, v16
	v_mul_hi_u32 v16, v17, v16
	v_mul_lo_u32 v19, v16, v18
	v_sub_u32_e32 v19, v17, v19
	v_add_u32_e32 v20, 1, v16
	v_cmp_ge_u32_e32 vcc, v19, v18
	v_add_u32_e32 v17, 1, v17
	s_nop 0
	v_cndmask_b32_e32 v16, v16, v20, vcc
	v_sub_u32_e32 v20, v19, v18
	v_cndmask_b32_e32 v19, v19, v20, vcc
	v_add_u32_e32 v20, 1, v16
	v_cmp_ge_u32_e32 vcc, v19, v18
	s_nop 1
	v_cndmask_b32_e32 v16, v16, v20, vcc
	v_mul_lo_u32 v19, v18, v16
	v_add_u32_e32 v18, v19, v18
	v_cmp_ne_u32_e32 vcc, v17, v18
	s_and_saveexec_b64 s[0:1], vcc
	s_xor_b64 s[8:9], exec, s[0:1]
	s_cbranch_execz .LBB0_101
	s_add_u32 s10, s70, 0x3500
	s_addc_u32 s11, s71, 0
	v_mov_b32_e32 v17, 0
	global_load_dword v17, v17, s[10:11] sc1
	s_waitcnt vmcnt(0)
	v_cmp_eq_u32_e32 vcc, v17, v16
	s_and_saveexec_b64 s[28:29], vcc
	s_cbranch_execz .LBB0_100
	s_mov_b64 s[30:31], 0
	v_mov_b32_e32 v17, 0

.LBB0_569:
	s_or_b64 exec, exec, s[10:11]
	s_cmp_eq_u32 s0, 0
	s_cselect_b64 vcc, -1, 0
	s_cmp_eq_u32 s0, 1
	v_cndmask_b32_e32 v18, 1, v15, vcc
	s_cselect_b64 vcc, -1, 0
	s_cmp_eq_u32 s0, 2
	v_cndmask_b32_e32 v18, v18, v0, vcc
	s_cselect_b64 vcc, -1, 0
	s_cmp_eq_u32 s0, 3
	v_cndmask_b32_e32 v18, v18, v1, vcc
	s_cselect_b64 vcc, -1, 0
	s_cmp_eq_u32 s0, 4
	v_cndmask_b32_e32 v18, v18, v2, vcc
	s_cselect_b64 vcc, -1, 0
	s_cmp_eq_u32 s0, 5
	v_cndmask_b32_e32 v18, v18, v3, vcc
	s_cselect_b64 vcc, -1, 0
	s_cmp_eq_u32 s0, 6
	v_cndmask_b32_e32 v18, v18, v4, vcc
	s_cselect_b64 vcc, -1, 0
	s_cmp_eq_u32 s0, 7
	v_cndmask_b32_e32 v18, v18, v5, vcc
	s_cselect_b64 vcc, -1, 0
	s_cmp_eq_u32 s0, 8
	v_cndmask_b32_e32 v18, v18, v6, vcc
	s_cselect_b64 vcc, -1, 0
	s_cmp_eq_u32 s0, 9
	v_cndmask_b32_e32 v18, v18, v7, vcc
	s_cselect_b64 vcc, -1, 0
	s_cmp_eq_u32 s0, 10
	v_cndmask_b32_e32 v18, v18, v8, vcc
	s_cselect_b64 vcc, -1, 0
	s_cmp_eq_u32 s0, 11
	v_cndmask_b32_e32 v18, v18, v9, vcc
	s_cselect_b64 vcc, -1, 0
	s_cmp_eq_u32 s0, 12
	v_cndmask_b32_e32 v18, v18, v10, vcc
	s_cselect_b64 vcc, -1, 0
	s_cmp_eq_u32 s0, 13
	v_cndmask_b32_e32 v18, v18, v11, vcc
	s_cselect_b64 vcc, -1, 0
	s_cmp_eq_u32 s0, 14
	v_cndmask_b32_e32 v18, v18, v12, vcc
	s_cselect_b64 vcc, -1, 0
	s_cmp_eq_u32 s0, 15
	v_cndmask_b32_e32 v18, v18, v13, vcc
	s_cselect_b64 vcc, -1, 0
	v_cndmask_b32_e32 v18, v18, v14, vcc
	v_cvt_f32_u32_e32 v19, v18
	s_waitcnt vmcnt(0)
	v_readfirstlane_b32 s0, v17
	v_rcp_iflag_f32_e32 v19, v19
	s_nop 0
	v_add_u32_e32 v17, s0, v16
	v_sub_u32_e32 v16, 0, v18
	v_mul_f32_e32 v19, 0x4f7ffffe, v19
	v_cvt_u32_f32_e32 v19, v19
	v_mul_lo_u32 v16, v16, v19
	v_mul_hi_u32 v16, v19, v16
	v_add_u32_e32 v16, v19, v16
	v_mul_hi_u32 v16, v17, v16
	v_mul_lo_u32 v19, v16, v18
	v_sub_u32_e32 v19, v17, v19
	v_add_u32_e32 v20, 1, v16
	v_cmp_ge_u32_e32 vcc, v19, v18
	v_add_u32_e32 v17, 1, v17
	s_nop 0
	v_cndmask_b32_e32 v16, v16, v20, vcc
	v_sub_u32_e32 v20, v19, v18
	v_cndmask_b32_e32 v19, v19, v20, vcc
	v_add_u32_e32 v20, 1, v16
	v_cmp_ge_u32_e32 vcc, v19, v18
	s_nop 1
	v_cndmask_b32_e32 v16, v16, v20, vcc
	v_mul_lo_u32 v19, v18, v16
	v_add_u32_e32 v18, v19, v18
	v_cmp_ne_u32_e32 vcc, v17, v18
	s_and_saveexec_b64 s[0:1], vcc
	s_xor_b64 s[8:9], exec, s[0:1]
	s_cbranch_execz .LBB0_574
	s_add_u32 s10, s70, 0x3500
	s_addc_u32 s11, s71, 0
	v_mov_b32_e32 v17, 0
	global_load_dword v17, v17, s[10:11] sc1
	s_waitcnt vmcnt(0)
	v_cmp_eq_u32_e32 vcc, v17, v16
	s_and_saveexec_b64 s[12:13], vcc
	s_cbranch_execz .LBB0_573
	s_mov_b64 s[14:15], 0
	v_mov_b32_e32 v17, 0

.LBB0_878:
	s_or_b64 exec, exec, s[10:11]
	s_cmp_eq_u32 s0, 0
	s_cselect_b64 vcc, -1, 0
	s_cmp_eq_u32 s0, 1
	v_cndmask_b32_e32 v18, 1, v15, vcc
	s_cselect_b64 vcc, -1, 0
	s_cmp_eq_u32 s0, 2
	v_cndmask_b32_e32 v18, v18, v0, vcc
	s_cselect_b64 vcc, -1, 0
	s_cmp_eq_u32 s0, 3
	v_cndmask_b32_e32 v18, v18, v1, vcc
	s_cselect_b64 vcc, -1, 0
	s_cmp_eq_u32 s0, 4
	v_cndmask_b32_e32 v18, v18, v2, vcc
	s_cselect_b64 vcc, -1, 0
	s_cmp_eq_u32 s0, 5
	v_cndmask_b32_e32 v18, v18, v3, vcc
	s_cselect_b64 vcc, -1, 0
	s_cmp_eq_u32 s0, 6
	v_cndmask_b32_e32 v18, v18, v4, vcc
	s_cselect_b64 vcc, -1, 0
	s_cmp_eq_u32 s0, 7
	v_cndmask_b32_e32 v18, v18, v5, vcc
	s_cselect_b64 vcc, -1, 0
	s_cmp_eq_u32 s0, 8
	v_cndmask_b32_e32 v18, v18, v6, vcc
	s_cselect_b64 vcc, -1, 0
	s_cmp_eq_u32 s0, 9
	v_cndmask_b32_e32 v18, v18, v7, vcc
	s_cselect_b64 vcc, -1, 0
	s_cmp_eq_u32 s0, 10
	v_cndmask_b32_e32 v18, v18, v8, vcc
	s_cselect_b64 vcc, -1, 0
	s_cmp_eq_u32 s0, 11
	v_cndmask_b32_e32 v18, v18, v9, vcc
	s_cselect_b64 vcc, -1, 0
	s_cmp_eq_u32 s0, 12
	v_cndmask_b32_e32 v18, v18, v10, vcc
	s_cselect_b64 vcc, -1, 0
	s_cmp_eq_u32 s0, 13
	v_cndmask_b32_e32 v18, v18, v11, vcc
	s_cselect_b64 vcc, -1, 0
	s_cmp_eq_u32 s0, 14
	v_cndmask_b32_e32 v18, v18, v12, vcc
	s_cselect_b64 vcc, -1, 0
	s_cmp_eq_u32 s0, 15
	v_cndmask_b32_e32 v18, v18, v13, vcc
	s_cselect_b64 vcc, -1, 0
	v_cndmask_b32_e32 v18, v18, v14, vcc
	v_cvt_f32_u32_e32 v19, v18
	s_waitcnt vmcnt(0)
	v_readfirstlane_b32 s0, v17
	v_rcp_iflag_f32_e32 v19, v19
	s_nop 0
	v_add_u32_e32 v17, s0, v16
	v_sub_u32_e32 v16, 0, v18
	v_mul_f32_e32 v19, 0x4f7ffffe, v19
	v_cvt_u32_f32_e32 v19, v19
	v_mul_lo_u32 v16, v16, v19
	v_mul_hi_u32 v16, v19, v16
	v_add_u32_e32 v16, v19, v16
	v_mul_hi_u32 v16, v17, v16
	v_mul_lo_u32 v19, v16, v18
	v_sub_u32_e32 v19, v17, v19
	v_add_u32_e32 v20, 1, v16
	v_cmp_ge_u32_e32 vcc, v19, v18
	v_add_u32_e32 v17, 1, v17
	s_nop 0
	v_cndmask_b32_e32 v16, v16, v20, vcc
	v_sub_u32_e32 v20, v19, v18
	v_cndmask_b32_e32 v19, v19, v20, vcc
	v_add_u32_e32 v20, 1, v16
	v_cmp_ge_u32_e32 vcc, v19, v18
	s_nop 1
	v_cndmask_b32_e32 v16, v16, v20, vcc
	v_mul_lo_u32 v19, v18, v16
	v_add_u32_e32 v18, v19, v18
	v_cmp_ne_u32_e32 vcc, v17, v18
	s_and_saveexec_b64 s[0:1], vcc
	s_xor_b64 s[8:9], exec, s[0:1]
	s_cbranch_execz .LBB0_883
	s_add_u32 s10, s70, 0x3500
	s_addc_u32 s11, s71, 0
	v_mov_b32_e32 v17, 0
	global_load_dword v17, v17, s[10:11] sc1
	s_waitcnt vmcnt(0)
	v_cmp_eq_u32_e32 vcc, v17, v16
	s_and_saveexec_b64 s[14:15], vcc
	s_cbranch_execz .LBB0_882
	s_mov_b64 s[20:21], 0
	v_mov_b32_e32 v17, 0

.LBB0_1403:
	s_or_b64 exec, exec, s[12:13]
	s_cmp_eq_u32 s0, 0
	s_cselect_b64 vcc, -1, 0
	s_cmp_eq_u32 s0, 1
	v_cndmask_b32_e32 v18, 1, v15, vcc
	s_cselect_b64 vcc, -1, 0
	s_cmp_eq_u32 s0, 2
	v_cndmask_b32_e32 v18, v18, v0, vcc
	s_cselect_b64 vcc, -1, 0
	s_cmp_eq_u32 s0, 3
	v_cndmask_b32_e32 v18, v18, v1, vcc
	s_cselect_b64 vcc, -1, 0
	s_cmp_eq_u32 s0, 4
	v_cndmask_b32_e32 v18, v18, v2, vcc
	s_cselect_b64 vcc, -1, 0
	s_cmp_eq_u32 s0, 5
	v_cndmask_b32_e32 v18, v18, v3, vcc
	s_cselect_b64 vcc, -1, 0
	s_cmp_eq_u32 s0, 6
	v_cndmask_b32_e32 v18, v18, v4, vcc
	s_cselect_b64 vcc, -1, 0
	s_cmp_eq_u32 s0, 7
	v_cndmask_b32_e32 v18, v18, v5, vcc
	s_cselect_b64 vcc, -1, 0
	s_cmp_eq_u32 s0, 8
	v_cndmask_b32_e32 v18, v18, v6, vcc
	s_cselect_b64 vcc, -1, 0
	s_cmp_eq_u32 s0, 9
	v_cndmask_b32_e32 v18, v18, v7, vcc
	s_cselect_b64 vcc, -1, 0
	s_cmp_eq_u32 s0, 10
	v_cndmask_b32_e32 v18, v18, v8, vcc
	s_cselect_b64 vcc, -1, 0
	s_cmp_eq_u32 s0, 11
	v_cndmask_b32_e32 v18, v18, v9, vcc
	s_cselect_b64 vcc, -1, 0
	s_cmp_eq_u32 s0, 12
	v_cndmask_b32_e32 v18, v18, v10, vcc
	s_cselect_b64 vcc, -1, 0
	s_cmp_eq_u32 s0, 13
	v_cndmask_b32_e32 v18, v18, v11, vcc
	s_cselect_b64 vcc, -1, 0
	s_cmp_eq_u32 s0, 14
	v_cndmask_b32_e32 v18, v18, v12, vcc
	s_cselect_b64 vcc, -1, 0
	s_cmp_eq_u32 s0, 15
	v_cndmask_b32_e32 v18, v18, v13, vcc
	s_cselect_b64 vcc, -1, 0
	v_cndmask_b32_e32 v18, v18, v14, vcc
	v_cvt_f32_u32_e32 v19, v18
	s_waitcnt vmcnt(0)
	v_readfirstlane_b32 s0, v17
	v_rcp_iflag_f32_e32 v19, v19
	s_nop 0
	v_add_u32_e32 v17, s0, v16
	v_sub_u32_e32 v16, 0, v18
	v_mul_f32_e32 v19, 0x4f7ffffe, v19
	v_cvt_u32_f32_e32 v19, v19
	v_mul_lo_u32 v16, v16, v19
	v_mul_hi_u32 v16, v19, v16
	v_add_u32_e32 v16, v19, v16
	v_mul_hi_u32 v16, v17, v16
	v_mul_lo_u32 v19, v16, v18
	v_sub_u32_e32 v19, v17, v19
	v_add_u32_e32 v20, 1, v16
	v_cmp_ge_u32_e32 vcc, v19, v18
	v_add_u32_e32 v17, 1, v17
	s_nop 0
	v_cndmask_b32_e32 v16, v16, v20, vcc
	v_sub_u32_e32 v20, v19, v18
	v_cndmask_b32_e32 v19, v19, v20, vcc
	v_add_u32_e32 v20, 1, v16
	v_cmp_ge_u32_e32 vcc, v19, v18
	s_nop 1
	v_cndmask_b32_e32 v16, v16, v20, vcc
	v_mul_lo_u32 v19, v18, v16
	v_add_u32_e32 v18, v19, v18
	v_cmp_ne_u32_e32 vcc, v17, v18
	s_and_saveexec_b64 s[0:1], vcc
	s_xor_b64 s[10:11], exec, s[0:1]
	s_cbranch_execz .LBB0_1408
	s_add_u32 s12, s70, 0x3500
	s_addc_u32 s13, s71, 0
	v_mov_b32_e32 v17, 0
	global_load_dword v17, v17, s[12:13] sc1
	s_waitcnt vmcnt(0)
	v_cmp_eq_u32_e32 vcc, v17, v16
	s_and_saveexec_b64 s[14:15], vcc
	s_cbranch_execz .LBB0_1407
	s_mov_b64 s[16:17], 0
	v_mov_b32_e32 v17, 0

.LBB0_1463:
	s_or_b64 exec, exec, s[8:9]
	s_cmp_eq_u32 s5, 0
	s_cselect_b64 vcc, -1, 0
	s_cmp_eq_u32 s5, 1
	v_cndmask_b32_e32 v18, 1, v15, vcc
	s_cselect_b64 vcc, -1, 0
	s_cmp_eq_u32 s5, 2
	v_cndmask_b32_e32 v18, v18, v0, vcc
	s_cselect_b64 vcc, -1, 0
	s_cmp_eq_u32 s5, 3
	v_cndmask_b32_e32 v18, v18, v1, vcc
	s_cselect_b64 vcc, -1, 0
	s_cmp_eq_u32 s5, 4
	v_cndmask_b32_e32 v18, v18, v2, vcc
	s_cselect_b64 vcc, -1, 0
	s_cmp_eq_u32 s5, 5
	v_cndmask_b32_e32 v18, v18, v3, vcc
	s_cselect_b64 vcc, -1, 0
	s_cmp_eq_u32 s5, 6
	v_cndmask_b32_e32 v18, v18, v4, vcc
	s_cselect_b64 vcc, -1, 0
	s_cmp_eq_u32 s5, 7
	v_cndmask_b32_e32 v18, v18, v5, vcc
	s_cselect_b64 vcc, -1, 0
	s_cmp_eq_u32 s5, 8
	v_cndmask_b32_e32 v18, v18, v6, vcc
	s_cselect_b64 vcc, -1, 0
	s_cmp_eq_u32 s5, 9
	v_cndmask_b32_e32 v18, v18, v7, vcc
	s_cselect_b64 vcc, -1, 0
	s_cmp_eq_u32 s5, 10
	v_cndmask_b32_e32 v18, v18, v8, vcc
	s_cselect_b64 vcc, -1, 0
	s_cmp_eq_u32 s5, 11
	v_cndmask_b32_e32 v18, v18, v9, vcc
	s_cselect_b64 vcc, -1, 0
	s_cmp_eq_u32 s5, 12
	v_cndmask_b32_e32 v18, v18, v10, vcc
	s_cselect_b64 vcc, -1, 0
	s_cmp_eq_u32 s5, 13
	v_cndmask_b32_e32 v18, v18, v11, vcc
	s_cselect_b64 vcc, -1, 0
	s_cmp_eq_u32 s5, 14
	v_cndmask_b32_e32 v18, v18, v12, vcc
	s_cselect_b64 vcc, -1, 0
	s_cmp_eq_u32 s5, 15
	v_cndmask_b32_e32 v18, v18, v13, vcc
	s_cselect_b64 vcc, -1, 0
	v_cndmask_b32_e32 v18, v18, v14, vcc
	v_cvt_f32_u32_e32 v19, v18
	s_waitcnt vmcnt(0)
	v_readfirstlane_b32 s5, v17
	v_rcp_iflag_f32_e32 v19, v19
	s_nop 0
	v_add_u32_e32 v17, s5, v16
	v_sub_u32_e32 v16, 0, v18
	v_mul_f32_e32 v19, 0x4f7ffffe, v19
	v_cvt_u32_f32_e32 v19, v19
	v_mul_lo_u32 v16, v16, v19
	v_mul_hi_u32 v16, v19, v16
	v_add_u32_e32 v16, v19, v16
	v_mul_hi_u32 v16, v17, v16
	v_mul_lo_u32 v19, v16, v18
	v_sub_u32_e32 v19, v17, v19
	v_add_u32_e32 v20, 1, v16
	v_cmp_ge_u32_e32 vcc, v19, v18
	v_add_u32_e32 v17, 1, v17
	s_nop 0
	v_cndmask_b32_e32 v16, v16, v20, vcc
	v_sub_u32_e32 v20, v19, v18
	v_cndmask_b32_e32 v19, v19, v20, vcc
	v_add_u32_e32 v20, 1, v16
	v_cmp_ge_u32_e32 vcc, v19, v18
	s_nop 1
	v_cndmask_b32_e32 v16, v16, v20, vcc
	v_mul_lo_u32 v19, v18, v16
	v_add_u32_e32 v18, v19, v18
	v_cmp_ne_u32_e32 vcc, v17, v18
	s_and_saveexec_b64 s[6:7], vcc
	s_xor_b64 s[6:7], exec, s[6:7]
	s_cbranch_execz .LBB0_1468
	s_add_u32 s8, s70, 0x3500
	s_addc_u32 s9, s71, 0
	v_mov_b32_e32 v17, 0
	global_load_dword v17, v17, s[8:9] sc1
	s_waitcnt vmcnt(0)
	v_cmp_eq_u32_e32 vcc, v17, v16
	s_and_saveexec_b64 s[10:11], vcc
	s_cbranch_execz .LBB0_1467
	s_mov_b64 s[12:13], 0
	v_mov_b32_e32 v17, 0
